# v37_scanedge
# speedup vs baseline: 1.0098x; 1.0038x over previous
; #define LAS __attribute__((address_space(3)))
; __device__ __forceinline__ unsigned cvt_pk_bf16(float lo, float hi) { unsigned r; asm volatile("v_cvt_pk_bf16_f32 %0, %1, %2" : "=v"(r) : "v"(lo), "v"(hi)); return r; }
; #define LDS_WAIT() asm volatile("s_waitcnt lgkmcnt(0)" ::: "memory")
; __device__ __forceinline__ void phase_scan(const Params& p, LAS unsigned char* lds, int wave, int lane, int G) {
;     ...
; #pragma unroll
;             for (int tt = 0; tt < 32; ++tt) { const f32x2 bu = *(const LAS f32x2*)(BuL + tt * 132 + 2 * lane);
;                 const float nr = a_re * s_re - a_im * s_im + bu.x, ni = a_re * s_im + a_im * s_re + bu.y; s_re = nr; s_im = ni;
;                 *(LAS unsigned*)(SLb + tt * 272 + 4 * lane) = cvt_pk_bf16(nr, ni); }
;             LDS_WAIT();
.Lscan_nopf:
	ds_read_b64 v[120:121], v101 offset:3696
	s_waitcnt lgkmcnt(7)
	v_fma_f32 v124, v74, v86, v106
	v_fma_f32 v125, v74, v87, v107
	v_fma_f32 v122, -v75, v87, v124
	v_fma_f32 v123, v75, v86, v125
	v_cvt_pk_bf16_f32 v140, v122, v123
	ds_write_b32 v102, v140 offset:16896
	ds_read_b64 v[106:107], v101 offset:4224
	s_waitcnt lgkmcnt(8)
	v_fma_f32 v124, v74, v122, v108
	v_fma_f32 v125, v74, v123, v109
	v_fma_f32 v86, -v75, v123, v124
	v_fma_f32 v87, v75, v122, v125
	v_cvt_pk_bf16_f32 v141, v86, v87
	ds_write_b32 v102, v141 offset:17168
	ds_read_b64 v[108:109], v101 offset:4752
	s_waitcnt lgkmcnt(9)
	v_fma_f32 v124, v74, v86, v110
	v_fma_f32 v125, v74, v87, v111
	v_fma_f32 v122, -v75, v87, v124
	v_fma_f32 v123, v75, v86, v125
	v_cvt_pk_bf16_f32 v140, v122, v123
	ds_write_b32 v102, v140 offset:17440
	ds_read_b64 v[110:111], v101 offset:5280
	s_waitcnt lgkmcnt(10)
	v_fma_f32 v124, v74, v122, v112
	v_fma_f32 v125, v74, v123, v113
	v_fma_f32 v86, -v75, v123, v124
	v_fma_f32 v87, v75, v122, v125
	v_cvt_pk_bf16_f32 v141, v86, v87
	ds_write_b32 v102, v141 offset:17712
	ds_read_b64 v[112:113], v101 offset:5808
	s_waitcnt lgkmcnt(11)
	v_fma_f32 v124, v74, v86, v114
	v_fma_f32 v125, v74, v87, v115
	v_fma_f32 v122, -v75, v87, v124
	v_fma_f32 v123, v75, v86, v125
	v_cvt_pk_bf16_f32 v140, v122, v123
	ds_write_b32 v102, v140 offset:17984
	ds_read_b64 v[114:115], v101 offset:6336
	s_waitcnt lgkmcnt(12)
	v_fma_f32 v124, v74, v122, v116
	v_fma_f32 v125, v74, v123, v117
	v_fma_f32 v86, -v75, v123, v124
	v_fma_f32 v87, v75, v122, v125
	v_cvt_pk_bf16_f32 v141, v86, v87
	ds_write_b32 v102, v141 offset:18256
	ds_read_b64 v[116:117], v101 offset:6864
	s_waitcnt lgkmcnt(13)
	v_fma_f32 v124, v74, v86, v118
	v_fma_f32 v125, v74, v87, v119
	v_fma_f32 v122, -v75, v87, v124
	v_fma_f32 v123, v75, v86, v125
	v_cvt_pk_bf16_f32 v140, v122, v123
	ds_write_b32 v102, v140 offset:18528
	ds_read_b64 v[118:119], v101 offset:7392
	s_waitcnt lgkmcnt(14)
	v_fma_f32 v124, v74, v122, v120
	v_fma_f32 v125, v74, v123, v121
	v_fma_f32 v86, -v75, v123, v124
	v_fma_f32 v87, v75, v122, v125
	v_cvt_pk_bf16_f32 v141, v86, v87
	ds_write_b32 v102, v141 offset:18800
	ds_read_b64 v[120:121], v101 offset:7920
	s_waitcnt lgkmcnt(14)
	v_fma_f32 v124, v74, v86, v106
	v_fma_f32 v125, v74, v87, v107
	v_fma_f32 v122, -v75, v87, v124
	v_fma_f32 v123, v75, v86, v125
	v_cvt_pk_bf16_f32 v140, v122, v123
	ds_write_b32 v102, v140 offset:19072
	ds_read_b64 v[106:107], v101 offset:8448
	s_waitcnt lgkmcnt(14)
	v_fma_f32 v124, v74, v122, v108
	v_fma_f32 v125, v74, v123, v109
	v_fma_f32 v86, -v75, v123, v124
	v_fma_f32 v87, v75, v122, v125
	v_cvt_pk_bf16_f32 v141, v86, v87
	ds_write_b32 v102, v141 offset:19344
	ds_read_b64 v[108:109], v101 offset:8976
	s_waitcnt lgkmcnt(14)
	v_fma_f32 v124, v74, v86, v110
	v_fma_f32 v125, v74, v87, v111
	v_fma_f32 v122, -v75, v87, v124
	v_fma_f32 v123, v75, v86, v125
	v_cvt_pk_bf16_f32 v140, v122, v123
	ds_write_b32 v102, v140 offset:19616
	ds_read_b64 v[110:111], v101 offset:9504
	s_waitcnt lgkmcnt(14)
	v_fma_f32 v124, v74, v122, v112
	v_fma_f32 v125, v74, v123, v113
	v_fma_f32 v86, -v75, v123, v124
	v_fma_f32 v87, v75, v122, v125
	v_cvt_pk_bf16_f32 v141, v86, v87
	ds_write_b32 v102, v141 offset:19888
	ds_read_b64 v[112:113], v101 offset:10032
	s_waitcnt lgkmcnt(14)
	v_fma_f32 v124, v74, v86, v114
	v_fma_f32 v125, v74, v87, v115
	v_fma_f32 v122, -v75, v87, v124
	v_fma_f32 v123, v75, v86, v125
	v_cvt_pk_bf16_f32 v140, v122, v123
	ds_write_b32 v102, v140 offset:20160
	ds_read_b64 v[114:115], v101 offset:10560
	s_waitcnt lgkmcnt(14)
	v_fma_f32 v124, v74, v122, v116
	v_fma_f32 v125, v74, v123, v117
	v_fma_f32 v86, -v75, v123, v124
	v_fma_f32 v87, v75, v122, v125
	v_cvt_pk_bf16_f32 v141, v86, v87
	ds_write_b32 v102, v141 offset:20432
	ds_read_b64 v[116:117], v101 offset:11088
	s_waitcnt lgkmcnt(14)
	v_fma_f32 v124, v74, v86, v118
	v_fma_f32 v125, v74, v87, v119
	v_fma_f32 v122, -v75, v87, v124
	v_fma_f32 v123, v75, v86, v125
	v_cvt_pk_bf16_f32 v140, v122, v123
	ds_write_b32 v102, v140 offset:20704
	ds_read_b64 v[118:119], v101 offset:11616
	s_waitcnt lgkmcnt(14)
	v_fma_f32 v124, v74, v122, v120
	v_fma_f32 v125, v74, v123, v121
	v_fma_f32 v86, -v75, v123, v124
	v_fma_f32 v87, v75, v122, v125
	v_cvt_pk_bf16_f32 v141, v86, v87
	ds_write_b32 v102, v141 offset:20976
	ds_read_b64 v[120:121], v101 offset:12144
	s_waitcnt lgkmcnt(14)
	v_fma_f32 v124, v74, v86, v106
	v_fma_f32 v125, v74, v87, v107
	v_fma_f32 v122, -v75, v87, v124
	v_fma_f32 v123, v75, v86, v125
	v_cvt_pk_bf16_f32 v140, v122, v123
	ds_write_b32 v102, v140 offset:21248
	ds_read_b64 v[106:107], v101 offset:12672
	s_waitcnt lgkmcnt(14)
	v_fma_f32 v124, v74, v122, v108
	v_fma_f32 v125, v74, v123, v109
	v_fma_f32 v86, -v75, v123, v124
	v_fma_f32 v87, v75, v122, v125
	v_cvt_pk_bf16_f32 v141, v86, v87
	ds_write_b32 v102, v141 offset:21520
	ds_read_b64 v[108:109], v101 offset:13200
	s_waitcnt lgkmcnt(14)
	v_fma_f32 v124, v74, v86, v110
	v_fma_f32 v125, v74, v87, v111
	v_fma_f32 v122, -v75, v87, v124
	v_fma_f32 v123, v75, v86, v125
	v_cvt_pk_bf16_f32 v140, v122, v123
	ds_write_b32 v102, v140 offset:21792
	ds_read_b64 v[110:111], v101 offset:13728
	s_waitcnt lgkmcnt(14)
	v_fma_f32 v124, v74, v122, v112
	v_fma_f32 v125, v74, v123, v113
	v_fma_f32 v86, -v75, v123, v124
	v_fma_f32 v87, v75, v122, v125
	v_cvt_pk_bf16_f32 v141, v86, v87
	ds_write_b32 v102, v141 offset:22064
	ds_read_b64 v[112:113], v101 offset:14256
	s_waitcnt lgkmcnt(14)
	v_fma_f32 v124, v74, v86, v114
	v_fma_f32 v125, v74, v87, v115
	v_fma_f32 v122, -v75, v87, v124
	v_fma_f32 v123, v75, v86, v125
	v_cvt_pk_bf16_f32 v140, v122, v123
	ds_write_b32 v102, v140 offset:22336
	ds_read_b64 v[114:115], v101 offset:14784
	s_waitcnt lgkmcnt(14)
; #define LAS __attribute__((address_space(3)))
; __device__ __forceinline__ unsigned cvt_pk_bf16(float lo, float hi) { unsigned r; asm volatile("v_cvt_pk_bf16_f32 %0, %1, %2" : "=v"(r) : "v"(lo), "v"(hi)); return r; }
; __device__ __forceinline__ float bf_lo(unsigned w) { return __uint_as_float(w << 16); }
; __device__ __forceinline__ float bf_hi(unsigned w) { return __uint_as_float(w & 0xffff0000u); }
; __device__ __forceinline__ float gelu_t(float x) { const float u = 1.5957691216f * (x + 0.044715f * x * x * x); return x * sigm(u); }
; #define LDS_WAIT() asm volatile("s_waitcnt lgkmcnt(0)" ::: "memory")
; __device__ __forceinline__ void phase_scan(const Params& p, LAS unsigned char* lds, int wave, int lane, int G) {
;     ...
; #pragma unroll
;             for (int tt = 0; tt < 32; ++tt) { const f32x2 bu = *(const LAS f32x2*)(BuL + tt * 132 + 2 * lane);
;                 const float nr = a_re * s_re - a_im * s_im + bu.x, ni = a_re * s_im + a_im * s_re + bu.y; s_re = nr; s_im = ni;
;                 *(LAS unsigned*)(SLb + tt * 272 + 4 * lane) = cvt_pk_bf16(nr, ni); }
;             LDS_WAIT();
; #pragma unroll
;             for (int mt = 0; mt < 2; ++mt) { f32x4 y = {0.f, 0.f, 0.f, 0.f};
; #pragma unroll
;                 for (int ks = 0; ks < 4; ++ks) { const bf16x8 sf = *(const LAS bf16x8*)(SLb + (mt * 16 + r16) * 272 + (32 * ks + 8 * kq) * 2); y = __builtin_amdgcn_mfma_f32_16x16x32_bf16(cfr[ks], sf, y, 0, 0, 0); }
;                 const f32x4 uu = {bf_lo(uy[mt].x), bf_hi(uy[mt].x), bf_lo(uy[mt].y), bf_hi(uy[mt].y)};
;                 y += dv * uu;
;                 u32x2 w; w.x = cvt_pk_bf16(gelu_t(y[0]), gelu_t(y[1])); w.y = cvt_pk_bf16(gelu_t(y[2]), gelu_t(y[3]));
;                 *(u32x2*)(yb + (size_t)(t0 + mt * 16 + r16) * DSS) = w; }
;             LDS_WAIT();
;         }
;     }
	v_fma_f32 v124, v74, v122, v116
	v_fma_f32 v125, v74, v123, v117
	v_fma_f32 v86, -v75, v123, v124
	v_fma_f32 v87, v75, v122, v125
	v_cvt_pk_bf16_f32 v141, v86, v87
	ds_write_b32 v102, v141 offset:22608
	ds_read_b64 v[116:117], v101 offset:15312
	s_waitcnt lgkmcnt(14)
	v_fma_f32 v124, v74, v86, v118
	v_fma_f32 v125, v74, v87, v119
	v_fma_f32 v122, -v75, v87, v124
	v_fma_f32 v123, v75, v86, v125
	v_cvt_pk_bf16_f32 v140, v122, v123
	ds_write_b32 v102, v140 offset:22880
	ds_read_b64 v[118:119], v101 offset:15840
	s_waitcnt lgkmcnt(14)
	v_fma_f32 v124, v74, v122, v120
	v_fma_f32 v125, v74, v123, v121
	v_fma_f32 v86, -v75, v123, v124
	v_fma_f32 v87, v75, v122, v125
	v_cvt_pk_bf16_f32 v141, v86, v87
	ds_write_b32 v102, v141 offset:23152
	ds_read_b64 v[120:121], v101 offset:16368
	s_waitcnt lgkmcnt(14)
	v_fma_f32 v124, v74, v86, v106
	v_fma_f32 v125, v74, v87, v107
	v_fma_f32 v122, -v75, v87, v124
	v_fma_f32 v123, v75, v86, v125
	v_cvt_pk_bf16_f32 v140, v122, v123
	ds_write_b32 v102, v140 offset:23424
	s_waitcnt lgkmcnt(13)
	v_fma_f32 v124, v74, v122, v108
	v_fma_f32 v125, v74, v123, v109
	v_fma_f32 v86, -v75, v123, v124
	v_fma_f32 v87, v75, v122, v125
	v_cvt_pk_bf16_f32 v141, v86, v87
	ds_write_b32 v102, v141 offset:23696
	s_waitcnt lgkmcnt(12)
	v_fma_f32 v124, v74, v86, v110
	v_fma_f32 v125, v74, v87, v111
	v_fma_f32 v122, -v75, v87, v124
	v_fma_f32 v123, v75, v86, v125
	v_cvt_pk_bf16_f32 v140, v122, v123
	ds_write_b32 v102, v140 offset:23968
	s_waitcnt lgkmcnt(11)
	v_fma_f32 v124, v74, v122, v112
	v_fma_f32 v125, v74, v123, v113
	v_fma_f32 v86, -v75, v123, v124
	v_fma_f32 v87, v75, v122, v125
	v_cvt_pk_bf16_f32 v141, v86, v87
	ds_write_b32 v102, v141 offset:24240
	s_waitcnt lgkmcnt(10)
	v_fma_f32 v124, v74, v86, v114
	v_fma_f32 v125, v74, v87, v115
	v_fma_f32 v122, -v75, v87, v124
	v_fma_f32 v123, v75, v86, v125
	v_cvt_pk_bf16_f32 v140, v122, v123
	ds_write_b32 v102, v140 offset:24512
	s_waitcnt lgkmcnt(9)
	v_fma_f32 v124, v74, v122, v116
	v_fma_f32 v125, v74, v123, v117
	v_fma_f32 v86, -v75, v123, v124
	v_fma_f32 v87, v75, v122, v125
	v_cvt_pk_bf16_f32 v141, v86, v87
	ds_write_b32 v102, v141 offset:24784
	s_waitcnt lgkmcnt(8)
	v_fma_f32 v124, v74, v86, v118
	v_fma_f32 v125, v74, v87, v119
	v_fma_f32 v122, -v75, v87, v124
	v_fma_f32 v123, v75, v86, v125
	v_cvt_pk_bf16_f32 v140, v122, v123
	ds_write_b32 v102, v140 offset:25056
	s_waitcnt lgkmcnt(7)
	v_fma_f32 v124, v74, v122, v120
	v_fma_f32 v125, v74, v123, v121
	v_fma_f32 v86, -v75, v123, v124
	v_fma_f32 v87, v75, v122, v125
	v_cvt_pk_bf16_f32 v141, v86, v87
	ds_write_b32 v102, v141 offset:25328
	v_lshlrev_b32_e32 v58, 16, v84
	v_and_b32_e32 v59, 0xffff0000, v84
	s_waitcnt lgkmcnt(0)
	ds_read_b128 v[52:55], v103 offset:16896
	ds_read_b128 v[88:91], v103 offset:16960
	s_waitcnt lgkmcnt(1)
	v_mfma_f32_16x16x32_bf16 v[52:55], v[32:35], v[52:55], 0
	s_waitcnt lgkmcnt(0)
	v_mfma_f32_16x16x32_bf16 v[52:55], v[36:39], v[88:91], v[52:55]
	ds_read_b128 v[88:91], v103 offset:17024
	ds_read_b128 v[106:109], v103 offset:17088
	s_waitcnt lgkmcnt(1)
	v_mfma_f32_16x16x32_bf16 v[52:55], v[40:43], v[88:91], v[52:55]
	s_waitcnt lgkmcnt(0)
	v_mfma_f32_16x16x32_bf16 v[52:55], v[44:47], v[106:109], v[52:55]
	s_nop 7
	v_pk_fma_f32 v[52:53], v[48:49], v[58:59], v[52:53]
	s_nop 0
	v_mul_f32_e32 v58, 0x3d372713, v52
	v_mul_f32_e32 v58, v52, v58
	v_fma_f32 v58, v52, v58, v52
	v_mul_f32_e32 v58, 0x3fcc422a, v58
	v_mul_f32_e32 v58, 0xbfb8aa3b, v58
	v_exp_f32_e32 v59, v58
	v_lshlrev_b32_e32 v58, 16, v85
	v_add_f32_e32 v59, 1.0, v59
	v_rcp_f32_e32 v84, v59
	v_mul_f32_e32 v59, 0x3d372713, v53
	v_mul_f32_e32 v59, v53, v59
	v_fma_f32 v59, v53, v59, v53
	v_mul_f32_e32 v59, 0x3fcc422a, v59
	v_mul_f32_e32 v59, 0xbfb8aa3b, v59
	v_exp_f32_e32 v88, v59
	v_and_b32_e32 v59, 0xffff0000, v85
	v_pk_fma_f32 v[54:55], v[50:51], v[58:59], v[54:55]
	v_mul_f32_e32 v52, v52, v84
	v_mul_f32_e32 v59, 0x3d372713, v54
	v_mul_f32_e32 v84, 0x3d372713, v55
	v_mul_f32_e32 v59, v54, v59
	v_mul_f32_e32 v84, v55, v84
	v_fma_f32 v59, v54, v59, v54
	v_fma_f32 v84, v55, v84, v55
	v_mul_f32_e32 v59, 0x3fcc422a, v59
	v_mul_f32_e32 v84, 0x3fcc422a, v84
	v_mul_f32_e32 v59, 0xbfb8aa3b, v59
	v_mul_f32_e32 v84, 0xbfb8aa3b, v84
	v_exp_f32_e32 v59, v59
	v_exp_f32_e32 v84, v84
	v_add_f32_e32 v58, 1.0, v88
	v_rcp_f32_e32 v58, v58
	v_add_f32_e32 v59, 1.0, v59
	v_add_f32_e32 v84, 1.0, v84
	v_rcp_f32_e32 v59, v59
	v_rcp_f32_e32 v84, v84
	v_mul_f32_e32 v53, v53, v58
	v_cvt_pk_bf16_f32 v58, v52, v53
	v_mul_f32_e32 v52, v54, v59
	v_mul_f32_e32 v53, v55, v84
	v_cvt_pk_bf16_f32 v59, v52, v53
	ds_read_b128 v[52:55], v103 offset:21248
	ds_read_b128 v[88:91], v103 offset:21312
	s_waitcnt lgkmcnt(1)
	v_mfma_f32_16x16x32_bf16 v[52:55], v[32:35], v[52:55], 0
	v_lshl_add_u64 v[84:85], v[80:81], 0, s[14:15]
	v_lshl_add_u64 v[80:81], v[80:81], 0, s[36:37]
	s_waitcnt lgkmcnt(0)
	v_mfma_f32_16x16x32_bf16 v[52:55], v[36:39], v[88:91], v[52:55]
	ds_read_b128 v[88:91], v103 offset:21376
	ds_read_b128 v[106:109], v103 offset:21440
	s_waitcnt lgkmcnt(1)
	v_mfma_f32_16x16x32_bf16 v[52:55], v[40:43], v[88:91], v[52:55]
	v_lshlrev_b32_e32 v88, 16, v138
	v_and_b32_e32 v89, 0xffff0000, v138
	s_waitcnt lgkmcnt(0)
	v_mfma_f32_16x16x32_bf16 v[52:55], v[44:47], v[106:109], v[52:55]
	s_nop 7
	v_pk_fma_f32 v[52:53], v[48:49], v[88:89], v[52:53]
	v_add_co_u32_e32 v88, vcc, s61, v84
	v_mul_f32_e32 v56, 0x3d372713, v52
	v_mul_f32_e32 v56, v52, v56
	v_fma_f32 v56, v52, v56, v52
	v_mul_f32_e32 v56, 0x3fcc422a, v56
	v_mul_f32_e32 v56, 0xbfb8aa3b, v56
	v_exp_f32_e32 v90, v56
	v_addc_co_u32_e32 v89, vcc, 0, v85, vcc
	global_store_dwordx2 v[88:89], v[58:59], off
	v_add_f32_e32 v58, 1.0, v90
	v_rcp_f32_e32 v58, v58
	v_lshlrev_b32_e32 v56, 16, v139
	v_and_b32_e32 v57, 0xffff0000, v139
	v_mul_f32_e32 v59, 0x3d372713, v53
	v_pk_fma_f32 v[54:55], v[50:51], v[56:57], v[54:55]
	v_mul_f32_e32 v59, v53, v59
	v_mul_f32_e32 v52, v52, v58
	v_mul_f32_e32 v57, 0x3d372713, v54
	v_mul_f32_e32 v58, 0x3d372713, v55
	v_fma_f32 v59, v53, v59, v53
	v_mul_f32_e32 v57, v54, v57
	v_mul_f32_e32 v58, v55, v58
	v_mul_f32_e32 v59, 0x3fcc422a, v59
	v_fma_f32 v57, v54, v57, v54
	v_fma_f32 v58, v55, v58, v55
	v_mul_f32_e32 v59, 0xbfb8aa3b, v59
	v_mul_f32_e32 v57, 0x3fcc422a, v57
	v_mul_f32_e32 v58, 0x3fcc422a, v58
	v_exp_f32_e32 v59, v59
	v_mul_f32_e32 v57, 0xbfb8aa3b, v57
	v_mul_f32_e32 v58, 0xbfb8aa3b, v58
	v_exp_f32_e32 v57, v57
	v_exp_f32_e32 v58, v58
	v_add_f32_e32 v56, 1.0, v59
	v_rcp_f32_e32 v56, v56
	v_add_f32_e32 v57, 1.0, v57
	v_add_f32_e32 v58, 1.0, v58
	v_rcp_f32_e32 v57, v57
	v_rcp_f32_e32 v58, v58
	v_mul_f32_e32 v53, v53, v56
	v_cvt_pk_bf16_f32 v52, v52, v53
	v_mul_f32_e32 v53, v54, v57
	v_mul_f32_e32 v54, v55, v58
	v_cvt_pk_bf16_f32 v53, v53, v54
	v_add_co_u32_e32 v54, vcc, 0x2b124000, v84
	s_nop 1
	v_addc_co_u32_e32 v55, vcc, 0, v85, vcc
	global_store_dwordx2 v[54:55], v[52:53], off
	s_waitcnt lgkmcnt(0)
	s_cmp_eq_u32 s62, 0
	s_cbranch_scc0 .Lscan_top
	s_branch .LBB0_271
